# selected-block attention: the always-selected block 0 of the kv group is staged once per workgroup in LDS and read from there by every token (one sixteenth less L2 traffic)
# speedup vs baseline: 1.0136x; 1.0084x over previous
.LBB0_841:
	s_andn2_b64 vcc, exec, s[0:1]
	v_readlane_b32 s3, v254, 47
	s_cbranch_vccnz .LBB0_934
	s_mov_b64 s[22:23], exec
	s_and_b32 s2, s3, 1
	s_lshr_b32 s0, s3, 1
	s_and_b32 s0, s0, 3
	s_lshl_b32 s26, s0, 12
	s_add_i32 s27, s26, 0x1000
	v_readfirstlane_b32 s1, v220
	s_and_b32 s0, s3, -8
	s_add_i32 s0, s0, s1
	s_add_i32 s26, s26, s0
	s_lshl_b32 s0, s2, 6
	s_add_u32 s12, s12, s0
	s_addc_u32 s13, s13, 0
	s_lshl_b32 s0, s2, 21
	s_add_u32 s18, s18, s0
	s_addc_u32 s19, s19, 0
	s_add_u32 s16, s16, s0
	s_addc_u32 s17, s17, 0
	v_lshl_or_b32 v202, s2, 3, v200
	v_and_b32_e32 v140, 63, v208
	v_lshlrev_b32_e32 v140, 4, v140
	v_add_u32_e32 v141, 0x1000, v140
	s_mov_b32 s48, 0x3e38aa3b
	s_mov_b32 s49, 0x3e38aa3b
	s_mov_b32 s57, 0x20400
	v_mov_b32_e32 v179, 0xf149f2ca
	v_lshl_add_u32 v66, v202, 2, s57
	ds_read_b32 v178, v66 offset:1984
	s_barrier
	s_and_b32 s0, s1, 3
	s_lshl_b32 s0, s0, 11
	s_cmp_lt_u32 s1, 4
	s_cselect_b32 s40, s18, s16
	s_cselect_b32 s41, s19, s17
	s_cselect_b32 s2, 0, 0x2000
	s_add_u32 s40, s40, s0
	s_addc_u32 s41, s41, 0
	s_add_i32 s2, s2, s0
	s_mov_b32 m0, s2
	s_nop 0
	global_load_lds_dwordx4 v140, s[40:41]
	s_add_u32 s40, s40, 0x400
	s_addc_u32 s41, s41, 0
	s_add_i32 m0, s2, 0x400
	s_nop 0
	global_load_lds_dwordx4 v140, s[40:41]
	s_waitcnt vmcnt(0)
	s_barrier
	s_lshl_b32 s0, s26, 7
	s_add_u32 s38, s12, s0
	s_addc_u32 s39, s13, 0
	v_lshrrev_b32_e32 v144, 3, v199
	global_load_dword v176, v144, s[38:39]
	s_lshl_b32 s0, s26, 11
	s_add_u32 s54, s14, s0
	s_addc_u32 s55, s15, 0
	v_lshlrev_b32_e32 v67, 7, v202
	v_lshl_add_u32 v67, v198, 1, v67
	global_load_dwordx4 v[16:19], v67, s[54:55]
	global_load_dwordx4 v[20:23], v67, s[54:55] offset:64
	s_mov_b64 s[34:35], s[18:19]
	s_mov_b64 s[36:37], s[16:17]
	ds_read_b128 v[32:35], v140 offset:0
	ds_read_b128 v[36:39], v140 offset:1024
	ds_read_b128 v[40:43], v140 offset:2048
	ds_read_b128 v[44:47], v140 offset:3072
	ds_read_b128 v[48:51], v140 offset:4096
	ds_read_b128 v[52:55], v140 offset:5120
	ds_read_b128 v[56:59], v140 offset:6144
	ds_read_b128 v[60:63], v140 offset:7168
	ds_read_b128 v[100:103], v140 offset:8192
	ds_read_b128 v[104:107], v140 offset:9216
	ds_read_b128 v[108:111], v140 offset:10240
	ds_read_b128 v[112:115], v140 offset:11264
	ds_read_b128 v[116:119], v140 offset:12288
	ds_read_b128 v[120:123], v140 offset:13312
	ds_read_b128 v[124:127], v140 offset:14336
	ds_read_b128 v[128:131], v140 offset:15360
	s_lshr_b32 s0, s26, 6
	s_add_i32 s0, s0, 1
	s_min_i32 s28, s0, 16
	s_mov_b32 s29, 0
	s_mov_b32 s30, 0
	s_mov_b32 s51, 0
	v_mov_b32_e32 v196, 0xf149f2ca
	v_mov_b32_e32 v197, 0
	v_mov_b32_e32 v0, 0
	v_mov_b32_e32 v1, 0
	v_mov_b32_e32 v2, 0
	v_mov_b32_e32 v3, 0
	v_mov_b32_e32 v4, 0
	v_mov_b32_e32 v5, 0
	v_mov_b32_e32 v6, 0
	v_mov_b32_e32 v7, 0
	v_mov_b32_e32 v8, 0
	v_mov_b32_e32 v9, 0
	v_mov_b32_e32 v10, 0
	v_mov_b32_e32 v11, 0
	v_mov_b32_e32 v12, 0
	v_mov_b32_e32 v13, 0
	v_mov_b32_e32 v14, 0
	v_mov_b32_e32 v15, 0
	s_waitcnt lgkmcnt(0)
	v_mul_f32_e32 v178, 0x3fb8aa3b, v178
	s_waitcnt vmcnt(2)
.Lsel_stepA:
	s_add_i32 s1, s29, 1
	s_cmp_ge_i32 s1, s28
	s_cbranch_scc1 .Lsel_issue_lastA
	s_mov_b32 s50, 0
	s_nop 0
	v_readlane_b32 s0, v176, s1
	s_lshl_b32 s31, s0, 6
	s_lshl_b32 s0, s0, 13
	s_add_u32 s34, s18, s0
	s_addc_u32 s35, s19, 0
	s_add_u32 s36, s16, s0
	s_addc_u32 s37, s17, 0
	global_load_dwordx4 v[68:71], v140, s[34:35] offset:0
	global_load_dwordx4 v[72:75], v140, s[34:35] offset:1024
	global_load_dwordx4 v[76:79], v140, s[34:35] offset:2048
	global_load_dwordx4 v[80:83], v140, s[34:35] offset:3072
	global_load_dwordx4 v[84:87], v141, s[34:35] offset:0
	global_load_dwordx4 v[88:91], v141, s[34:35] offset:1024
	global_load_dwordx4 v[92:95], v141, s[34:35] offset:2048
	global_load_dwordx4 v[96:99], v141, s[34:35] offset:3072
	global_load_dwordx4 v[132:135], v140, s[36:37] offset:0
	global_load_dwordx4 v[136:139], v140, s[36:37] offset:1024
	global_load_dwordx4 v[148:151], v140, s[36:37] offset:2048
	global_load_dwordx4 v[152:155], v140, s[36:37] offset:3072
	global_load_dwordx4 v[156:159], v141, s[36:37] offset:0
	global_load_dwordx4 v[160:163], v141, s[36:37] offset:1024
	global_load_dwordx4 v[164:167], v141, s[36:37] offset:2048
	global_load_dwordx4 v[168:171], v141, s[36:37] offset:3072
	s_waitcnt vmcnt(16) lgkmcnt(0)
	s_branch .Lsel_computeA
.Lsel_issue_lastA:
	s_mov_b32 s50, 1
	s_lshl_b32 s0, s26, 7
	s_add_u32 s40, s20, s0
	s_addc_u32 s41, s21, 0
	v_mul_u32_u24_e32 v66, 6, v202
	global_load_ushort v64, v66, s[40:41]
	s_mul_i32 s0, s26, 0x1800
	s_add_i32 s0, s0, 0x1000
	s_add_u32 s40, s24, s0
	s_addc_u32 s41, s25, 0
	v_lshlrev_b32_e32 v67, 7, v202
	v_lshl_add_u32 v67, v182, 1, v67
	global_load_dwordx2 v[24:25], v67, s[40:41] offset:0
	global_load_dwordx2 v[26:27], v67, s[40:41] offset:32
	global_load_dwordx2 v[28:29], v67, s[40:41] offset:64
	global_load_dwordx2 v[30:31], v67, s[40:41] offset:96
	s_add_i32 s56, s26, 0x100
	s_cmp_lt_i32 s56, s27
	s_cselect_b32 s56, s56, s26
	s_lshl_b32 s0, s56, 7
	s_add_u32 s38, s12, s0
	s_addc_u32 s39, s13, 0
	s_lshl_b32 s0, s56, 11
	s_add_u32 s54, s14, s0
	s_addc_u32 s55, s15, 0
	v_lshrrev_b32_e32 v144, 3, v199
	global_load_dword v176, v144, s[38:39]
	s_mov_b32 s31, 0
	s_mov_b64 s[34:35], s[18:19]
	s_mov_b64 s[36:37], s[16:17]
	ds_read_b128 v[68:71], v140 offset:0
	ds_read_b128 v[72:75], v140 offset:1024
	ds_read_b128 v[76:79], v140 offset:2048
	ds_read_b128 v[80:83], v140 offset:3072
	ds_read_b128 v[84:87], v140 offset:4096
	ds_read_b128 v[88:91], v140 offset:5120
	ds_read_b128 v[92:95], v140 offset:6144
	ds_read_b128 v[96:99], v140 offset:7168
	ds_read_b128 v[132:135], v140 offset:8192
	ds_read_b128 v[136:139], v140 offset:9216
	ds_read_b128 v[148:151], v140 offset:10240
	ds_read_b128 v[152:155], v140 offset:11264
	ds_read_b128 v[156:159], v140 offset:12288
	ds_read_b128 v[160:163], v140 offset:13312
	ds_read_b128 v[164:167], v140 offset:14336
	ds_read_b128 v[168:171], v140 offset:15360
	s_waitcnt vmcnt(6)

.Lsel_stepB:
	s_add_i32 s1, s29, 1
	s_cmp_ge_i32 s1, s28
	s_cbranch_scc1 .Lsel_issue_lastB
	s_mov_b32 s50, 0
	s_nop 0
	v_readlane_b32 s0, v176, s1
	s_lshl_b32 s31, s0, 6
	s_lshl_b32 s0, s0, 13
	s_add_u32 s34, s18, s0
	s_addc_u32 s35, s19, 0
	s_add_u32 s36, s16, s0
	s_addc_u32 s37, s17, 0
	global_load_dwordx4 v[32:35], v140, s[34:35] offset:0
	global_load_dwordx4 v[36:39], v140, s[34:35] offset:1024
	global_load_dwordx4 v[40:43], v140, s[34:35] offset:2048
	global_load_dwordx4 v[44:47], v140, s[34:35] offset:3072
	global_load_dwordx4 v[48:51], v141, s[34:35] offset:0
	global_load_dwordx4 v[52:55], v141, s[34:35] offset:1024
	global_load_dwordx4 v[56:59], v141, s[34:35] offset:2048
	global_load_dwordx4 v[60:63], v141, s[34:35] offset:3072
	global_load_dwordx4 v[100:103], v140, s[36:37] offset:0
	global_load_dwordx4 v[104:107], v140, s[36:37] offset:1024
	global_load_dwordx4 v[108:111], v140, s[36:37] offset:2048
	global_load_dwordx4 v[112:115], v140, s[36:37] offset:3072
	global_load_dwordx4 v[116:119], v141, s[36:37] offset:0
	global_load_dwordx4 v[120:123], v141, s[36:37] offset:1024
	global_load_dwordx4 v[124:127], v141, s[36:37] offset:2048
	global_load_dwordx4 v[128:131], v141, s[36:37] offset:3072
	s_waitcnt vmcnt(16) lgkmcnt(0)
	s_branch .Lsel_computeB
.Lsel_issue_lastB:
	s_mov_b32 s50, 1
	s_lshl_b32 s0, s26, 7
	s_add_u32 s40, s20, s0
	s_addc_u32 s41, s21, 0
	v_mul_u32_u24_e32 v66, 6, v202
	global_load_ushort v64, v66, s[40:41]
	s_mul_i32 s0, s26, 0x1800
	s_add_i32 s0, s0, 0x1000
	s_add_u32 s40, s24, s0
	s_addc_u32 s41, s25, 0
	v_lshlrev_b32_e32 v67, 7, v202
	v_lshl_add_u32 v67, v182, 1, v67
	global_load_dwordx2 v[24:25], v67, s[40:41] offset:0
	global_load_dwordx2 v[26:27], v67, s[40:41] offset:32
	global_load_dwordx2 v[28:29], v67, s[40:41] offset:64
	global_load_dwordx2 v[30:31], v67, s[40:41] offset:96
	s_add_i32 s56, s26, 0x100
	s_cmp_lt_i32 s56, s27
	s_cselect_b32 s56, s56, s26
	s_lshl_b32 s0, s56, 7
	s_add_u32 s38, s12, s0
	s_addc_u32 s39, s13, 0
	s_lshl_b32 s0, s56, 11
	s_add_u32 s54, s14, s0
	s_addc_u32 s55, s15, 0
	v_lshrrev_b32_e32 v144, 3, v199
	global_load_dword v176, v144, s[38:39]
	s_mov_b32 s31, 0
	s_mov_b64 s[34:35], s[18:19]
	s_mov_b64 s[36:37], s[16:17]
	ds_read_b128 v[32:35], v140 offset:0
	ds_read_b128 v[36:39], v140 offset:1024
	ds_read_b128 v[40:43], v140 offset:2048
	ds_read_b128 v[44:47], v140 offset:3072
	ds_read_b128 v[48:51], v140 offset:4096
	ds_read_b128 v[52:55], v140 offset:5120
	ds_read_b128 v[56:59], v140 offset:6144
	ds_read_b128 v[60:63], v140 offset:7168
	ds_read_b128 v[100:103], v140 offset:8192
	ds_read_b128 v[104:107], v140 offset:9216
	ds_read_b128 v[108:111], v140 offset:10240
	ds_read_b128 v[112:115], v140 offset:11264
	ds_read_b128 v[116:119], v140 offset:12288
	ds_read_b128 v[120:123], v140 offset:13312
	ds_read_b128 v[124:127], v140 offset:14336
	ds_read_b128 v[128:131], v140 offset:15360
	s_waitcnt vmcnt(6)

.Lsel_epilogue:
	s_waitcnt vmcnt(3)
	s_nop 7
	ds_bpermute_b32 v66, v180, v197
	s_waitcnt lgkmcnt(0)
	v_add_f32_e32 v197, v197, v66
	ds_bpermute_b32 v66, v181, v197
	v_lshlrev_b32_e32 v67, 16, v64
	v_mul_f32_e32 v67, 0xbfb8aa3b, v67
	v_exp_f32_e32 v67, v67
	s_waitcnt lgkmcnt(0)
	v_add_f32_e32 v197, v197, v66
	v_add_f32_e32 v67, 1.0, v67
	v_mul_f32_e32 v67, v67, v197
	v_rcp_f32_e32 v67, v67
	s_nop 0
	v_lshlrev_b32_e32 v144, 16, v24
	v_and_b32_e32 v145, 0xffff0000, v24
	v_lshlrev_b32_e32 v143, 16, v25
	v_and_b32_e32 v177, 0xffff0000, v25
	v_fmac_f32_e32 v144, v0, v67
	v_fmac_f32_e32 v145, v1, v67
	v_fmac_f32_e32 v143, v2, v67
	v_fmac_f32_e32 v177, v3, v67
	v_cvt_pk_bf16_f32 v24, v144, v145
	v_cvt_pk_bf16_f32 v25, v143, v177
	v_lshlrev_b32_e32 v144, 16, v26
	v_and_b32_e32 v145, 0xffff0000, v26
	v_lshlrev_b32_e32 v143, 16, v27
	v_and_b32_e32 v177, 0xffff0000, v27
	v_fmac_f32_e32 v144, v4, v67
	v_fmac_f32_e32 v145, v5, v67
	v_fmac_f32_e32 v143, v6, v67
	v_fmac_f32_e32 v177, v7, v67
	v_cvt_pk_bf16_f32 v26, v144, v145
	v_cvt_pk_bf16_f32 v27, v143, v177
	v_lshlrev_b32_e32 v144, 16, v28
	v_and_b32_e32 v145, 0xffff0000, v28
	v_lshlrev_b32_e32 v143, 16, v29
	v_and_b32_e32 v177, 0xffff0000, v29
	v_fmac_f32_e32 v144, v8, v67
	v_fmac_f32_e32 v145, v9, v67
	v_fmac_f32_e32 v143, v10, v67
	v_fmac_f32_e32 v177, v11, v67
	v_cvt_pk_bf16_f32 v28, v144, v145
	v_cvt_pk_bf16_f32 v29, v143, v177
	v_lshlrev_b32_e32 v144, 16, v30
	v_and_b32_e32 v145, 0xffff0000, v30
	v_lshlrev_b32_e32 v143, 16, v31
	v_and_b32_e32 v177, 0xffff0000, v31
	v_fmac_f32_e32 v144, v12, v67
	v_fmac_f32_e32 v145, v13, v67
	v_fmac_f32_e32 v143, v14, v67
	v_fmac_f32_e32 v177, v15, v67
	v_cvt_pk_bf16_f32 v30, v144, v145
	v_cvt_pk_bf16_f32 v31, v143, v177
	v_lshlrev_b32_e32 v66, 7, v202
	v_lshl_add_u32 v66, v182, 1, v66
	s_and_saveexec_b64 s[0:1], s[8:9]
	global_store_dwordx2 v66, v[24:25], s[40:41] offset:0
	global_store_dwordx2 v66, v[26:27], s[40:41] offset:32
	global_store_dwordx2 v66, v[28:29], s[40:41] offset:64
	global_store_dwordx2 v66, v[30:31], s[40:41] offset:96
	s_mov_b64 exec, s[0:1]
	s_add_i32 s26, s26, 0x100
	s_cmp_ge_i32 s26, s27
	s_cbranch_scc1 .Lsel_exit
	s_lshr_b32 s0, s26, 6
	s_add_i32 s0, s0, 1
	s_min_i32 s28, s0, 16
	s_mov_b32 s29, 0
	s_mov_b32 s30, 0
	v_mov_b32_e32 v196, 0xf149f2ca
	v_mov_b32_e32 v197, 0
	v_mov_b32_e32 v0, 0
	v_mov_b32_e32 v1, 0
	v_mov_b32_e32 v2, 0
	v_mov_b32_e32 v3, 0
	v_mov_b32_e32 v4, 0
	v_mov_b32_e32 v5, 0
	v_mov_b32_e32 v6, 0
	v_mov_b32_e32 v7, 0
	v_mov_b32_e32 v8, 0
	v_mov_b32_e32 v9, 0
	v_mov_b32_e32 v10, 0
	v_mov_b32_e32 v11, 0
	v_mov_b32_e32 v12, 0
	v_mov_b32_e32 v13, 0
	v_mov_b32_e32 v14, 0
	v_mov_b32_e32 v15, 0
	s_waitcnt vmcnt(6)
	s_cmp_eq_u32 s51, 0
	s_cbranch_scc1 .Lsel_stepB
	s_branch .Lsel_stepA
